# v15 plus an early L2 writeback issued by the first workgroup of each XCD to arrive at the grid barrier after the chain/attention phase
# baseline (speedup 1.0000x reference)
.LBB0_1025:
	s_or_b64 exec, exec, s[8:9]
	v_cvt_f32_u32_e32 v4, v2
	s_waitcnt vmcnt(0)
	v_readfirstlane_b32 s6, v3
	v_sub_u32_e32 v3, 0, v2
	v_rcp_iflag_f32_e32 v4, v4
	v_add_u32_e32 v5, s6, v1
	v_mul_f32_e32 v4, 0x4f7ffffe, v4
	v_cvt_u32_f32_e32 v4, v4
	v_mul_lo_u32 v1, v3, v4
	v_mul_hi_u32 v1, v4, v1
	v_add_u32_e32 v1, v4, v1
	v_mul_hi_u32 v1, v5, v1
	v_mul_lo_u32 v3, v1, v2
	v_sub_u32_e32 v3, v5, v3
	v_add_u32_e32 v4, 1, v1
	v_cmp_ge_u32_e32 vcc, v3, v2
	s_nop 1
	v_cndmask_b32_e32 v1, v1, v4, vcc
	v_sub_u32_e32 v4, v3, v2
	v_cndmask_b32_e32 v3, v3, v4, vcc
	v_add_u32_e32 v4, 1, v1
	v_cmp_ge_u32_e32 vcc, v3, v2
	v_add_u32_e32 v3, 1, v5
	s_nop 0
	v_cndmask_b32_e32 v1, v1, v4, vcc
	v_mul_lo_u32 v4, v2, v1
	v_add_u32_e32 v2, v4, v2
	v_cmp_ne_u32_e32 vcc, v3, v2
	s_and_saveexec_b64 s[6:7], vcc
	s_xor_b64 s[6:7], exec, s[6:7]
	s_cbranch_execz .LBB0_1039
	v_cmp_eq_u32_e32 vcc, v5, v4
	s_cbranch_vccz .Lg4_noflush
	buffer_wbl2 sc1
.Lg4_noflush:
	s_waitcnt lgkmcnt(0)
	v_mov_b32_e32 v0, 0x2000
	global_load_dword v0, v0, s[4:5] offset:1024 sc1
	s_add_u32 s12, s4, 0x2400
	s_addc_u32 s13, s5, 0
	s_waitcnt vmcnt(0)
	v_cmp_eq_u32_e32 vcc, v0, v1
	s_and_saveexec_b64 s[8:9], vcc
	s_cbranch_execz .LBB0_1038
	s_add_u32 s10, s70, 0x4200
	s_addc_u32 s11, s71, 0
	s_mov_b32 s24, 1
	s_mov_b64 s[14:15], 0
	v_mov_b32_e32 v0, 0
	s_branch .LBB0_1029
